# ev_in gates segment (tile 36) handled in the fast path: one bias load + 32 masked stores instead of 8 serialized load/wait/store groups; odin V-seg code present but disabled
# speedup vs baseline: 1.0017x; 1.0017x over previous
.LBB0_268:
	s_lshr_b32 s24, s14, 9
	v_lshl_or_b32 v116, v183, 3, v191
	v_lshrrev_b32_e32 v117, 6, v116
	v_and_b32_e32 v118, 63, v116
	v_lshlrev_b32_e32 v113, 11, v117
	v_add_u32_e32 v113, 0x10000, v113
	v_readfirstlane_b32 s0, v117
	v_and_b32_e32 v116, 31, v118
	v_lshl_add_u32 v112, v116, 1, v113
	v_lshrrev_b32_e32 v117, 5, v118
	v_lshl_add_u32 v112, v117, 8, v112
	v_lshl_add_u32 v113, v118, 4, v113
	v_mul_u32_u24_e32 v115, 0x6000, v116
	v_lshl_add_u32 v115, v117, 3, v115
	v_lshrrev_b32_e32 v117, 2, v118
	v_mul_u32_u24_e32 v117, 0x1c00, v117
	v_and_b32_e32 v114, 3, v118
	v_lshl_add_u32 v114, v114, 4, v117
	s_lshr_b32 s1, s0, 1
	s_lshl_b32 s1, s1, 6
	s_add_u32 s1, s1, s13
	s_and_b32 s0, s0, 1
	s_lshl_b32 s0, s0, 6
	s_and_b32 s2, s14, 0x1ff
	s_add_u32 s0, s0, s2
	s_cmp_eq_u32 s24, 9
	s_cbranch_scc1 .Levin1_gates
	s_cmp_lg_u32 s24, 0
	s_cbranch_scc1 .Levin1_noscale
	v_mul_f32_e32 v48, 0x3db504f3, v48
	v_mul_f32_e32 v49, 0x3db504f3, v49
	v_mul_f32_e32 v50, 0x3db504f3, v50
	v_mul_f32_e32 v51, 0x3db504f3, v51
	v_mul_f32_e32 v52, 0x3db504f3, v52
	v_mul_f32_e32 v53, 0x3db504f3, v53
	v_mul_f32_e32 v54, 0x3db504f3, v54
	v_mul_f32_e32 v55, 0x3db504f3, v55
	v_mul_f32_e32 v56, 0x3db504f3, v56
	v_mul_f32_e32 v57, 0x3db504f3, v57
	v_mul_f32_e32 v58, 0x3db504f3, v58
	v_mul_f32_e32 v59, 0x3db504f3, v59
	v_mul_f32_e32 v60, 0x3db504f3, v60
	v_mul_f32_e32 v61, 0x3db504f3, v61
	v_mul_f32_e32 v62, 0x3db504f3, v62
	v_mul_f32_e32 v63, 0x3db504f3, v63
	v_mul_f32_e32 v16, 0x3db504f3, v16
	v_mul_f32_e32 v17, 0x3db504f3, v17
	v_mul_f32_e32 v18, 0x3db504f3, v18
	v_mul_f32_e32 v19, 0x3db504f3, v19
	v_mul_f32_e32 v20, 0x3db504f3, v20
	v_mul_f32_e32 v21, 0x3db504f3, v21
	v_mul_f32_e32 v22, 0x3db504f3, v22
	v_mul_f32_e32 v23, 0x3db504f3, v23
	v_mul_f32_e32 v24, 0x3db504f3, v24
	v_mul_f32_e32 v25, 0x3db504f3, v25
	v_mul_f32_e32 v26, 0x3db504f3, v26
	v_mul_f32_e32 v27, 0x3db504f3, v27
	v_mul_f32_e32 v28, 0x3db504f3, v28
	v_mul_f32_e32 v29, 0x3db504f3, v29
	v_mul_f32_e32 v30, 0x3db504f3, v30
	v_mul_f32_e32 v31, 0x3db504f3, v31
	v_mul_f32_e32 v32, 0x3db504f3, v32
	v_mul_f32_e32 v33, 0x3db504f3, v33
	v_mul_f32_e32 v34, 0x3db504f3, v34
	v_mul_f32_e32 v35, 0x3db504f3, v35
	v_mul_f32_e32 v36, 0x3db504f3, v36
	v_mul_f32_e32 v37, 0x3db504f3, v37
	v_mul_f32_e32 v38, 0x3db504f3, v38
	v_mul_f32_e32 v39, 0x3db504f3, v39
	v_mul_f32_e32 v40, 0x3db504f3, v40
	v_mul_f32_e32 v41, 0x3db504f3, v41
	v_mul_f32_e32 v42, 0x3db504f3, v42
	v_mul_f32_e32 v43, 0x3db504f3, v43
	v_mul_f32_e32 v44, 0x3db504f3, v44
	v_mul_f32_e32 v45, 0x3db504f3, v45
	v_mul_f32_e32 v46, 0x3db504f3, v46
	v_mul_f32_e32 v47, 0x3db504f3, v47
	v_mul_f32_e32 v0, 0x3db504f3, v0
	v_mul_f32_e32 v1, 0x3db504f3, v1
	v_mul_f32_e32 v2, 0x3db504f3, v2
	v_mul_f32_e32 v3, 0x3db504f3, v3
	v_mul_f32_e32 v4, 0x3db504f3, v4
	v_mul_f32_e32 v5, 0x3db504f3, v5
	v_mul_f32_e32 v6, 0x3db504f3, v6
	v_mul_f32_e32 v7, 0x3db504f3, v7
	v_mul_f32_e32 v8, 0x3db504f3, v8
	v_mul_f32_e32 v9, 0x3db504f3, v9
	v_mul_f32_e32 v10, 0x3db504f3, v10
	v_mul_f32_e32 v11, 0x3db504f3, v11
	v_mul_f32_e32 v12, 0x3db504f3, v12
	v_mul_f32_e32 v13, 0x3db504f3, v13
	v_mul_f32_e32 v14, 0x3db504f3, v14
	v_mul_f32_e32 v15, 0x3db504f3, v15

.Levin1_gates:
	s_and_b32 s2, s0, 0x40
	s_cmp_lg_u32 s2, 0
	s_cbranch_scc1 .LBB0_259
	v_readlane_b32 s98, v250, 17
	v_readlane_b32 s99, v250, 18
	v_and_b32_e32 v116, 31, v118
	v_lshlrev_b32_e32 v117, 2, v116
	v_lshrrev_b32_e32 v114, 5, v118
	v_lshl_add_u32 v114, v114, 8, v117
	v_cmp_gt_u32_e32 vcc, 16, v116
	s_and_saveexec_b64 s[100:101], vcc
	s_nop 3
	global_load_dword v64, v117, s[98:99]
	s_lshl_b32 s2, s1, 6
	s_add_u32 s2, s2, 0x346a100
	s_add_u32 s98, s90, s2
	s_addc_u32 s99, s91, 0
	s_waitcnt vmcnt(0)
	v_add_f32_e32 v65, v48, v64
	global_store_dword v114, v65, s[98:99]
	v_add_f32_e32 v66, v49, v64
	global_store_dword v114, v66, s[98:99] offset:64
	v_add_f32_e32 v67, v50, v64
	global_store_dword v114, v67, s[98:99] offset:128
	v_add_f32_e32 v68, v51, v64
	global_store_dword v114, v68, s[98:99] offset:192
	v_add_f32_e32 v69, v52, v64
	global_store_dword v114, v69, s[98:99] offset:512
	v_add_f32_e32 v70, v53, v64
	global_store_dword v114, v70, s[98:99] offset:576
	v_add_f32_e32 v71, v54, v64
	global_store_dword v114, v71, s[98:99] offset:640
	v_add_f32_e32 v72, v55, v64
	global_store_dword v114, v72, s[98:99] offset:704
	v_add_f32_e32 v73, v56, v64
	global_store_dword v114, v73, s[98:99] offset:1024
	v_add_f32_e32 v74, v57, v64
	global_store_dword v114, v74, s[98:99] offset:1088
	v_add_f32_e32 v75, v58, v64
	global_store_dword v114, v75, s[98:99] offset:1152
	v_add_f32_e32 v76, v59, v64
	global_store_dword v114, v76, s[98:99] offset:1216
	v_add_f32_e32 v77, v60, v64
	global_store_dword v114, v77, s[98:99] offset:1536
	v_add_f32_e32 v78, v61, v64
	global_store_dword v114, v78, s[98:99] offset:1600
	v_add_f32_e32 v79, v62, v64
	global_store_dword v114, v79, s[98:99] offset:1664
	v_add_f32_e32 v80, v63, v64
	global_store_dword v114, v80, s[98:99] offset:1728
	v_add_f32_e32 v81, v32, v64
	global_store_dword v114, v81, s[98:99] offset:2048
	v_add_f32_e32 v82, v33, v64
	global_store_dword v114, v82, s[98:99] offset:2112
	v_add_f32_e32 v83, v34, v64
	global_store_dword v114, v83, s[98:99] offset:2176
	v_add_f32_e32 v84, v35, v64
	global_store_dword v114, v84, s[98:99] offset:2240
	v_add_f32_e32 v85, v36, v64
	global_store_dword v114, v85, s[98:99] offset:2560
	v_add_f32_e32 v86, v37, v64
	global_store_dword v114, v86, s[98:99] offset:2624
	v_add_f32_e32 v87, v38, v64
	global_store_dword v114, v87, s[98:99] offset:2688
	v_add_f32_e32 v88, v39, v64
	global_store_dword v114, v88, s[98:99] offset:2752
	v_add_f32_e32 v89, v40, v64
	global_store_dword v114, v89, s[98:99] offset:3072
	v_add_f32_e32 v90, v41, v64
	global_store_dword v114, v90, s[98:99] offset:3136
	v_add_f32_e32 v91, v42, v64
	global_store_dword v114, v91, s[98:99] offset:3200
	v_add_f32_e32 v92, v43, v64
	global_store_dword v114, v92, s[98:99] offset:3264
	v_add_f32_e32 v93, v44, v64
	global_store_dword v114, v93, s[98:99] offset:3584
	v_add_f32_e32 v94, v45, v64
	global_store_dword v114, v94, s[98:99] offset:3648
	v_add_f32_e32 v95, v46, v64
	global_store_dword v114, v95, s[98:99] offset:3712
	v_add_f32_e32 v96, v47, v64
	global_store_dword v114, v96, s[98:99] offset:3776
	s_mov_b64 exec, s[100:101]
	s_branch .LBB0_259

.LBB0_1518:
	s_lshr_b32 s12, s10, 10
	s_cmp_gt_u32 s12, 1
	s_cbranch_scc1 .Lodin4_old
	v_lshl_or_b32 v116, v183, 3, v191
	v_lshrrev_b32_e32 v117, 6, v116
	v_and_b32_e32 v118, 63, v116
	v_lshlrev_b32_e32 v113, 11, v117
	v_add_u32_e32 v113, 0x10000, v113
	v_readfirstlane_b32 s6, v117
	v_and_b32_e32 v116, 31, v118
	v_lshl_add_u32 v112, v116, 1, v113
	v_lshrrev_b32_e32 v117, 5, v118
	v_lshl_add_u32 v112, v117, 8, v112
	v_lshl_add_u32 v113, v118, 4, v113
	v_lshlrev_b32_e32 v115, 2, v116
	v_lshl_add_u32 v115, v117, 14, v115
	v_lshrrev_b32_e32 v117, 2, v118
	v_and_b32_e32 v114, 3, v118
	v_lshlrev_b32_e32 v114, 4, v114
	v_lshl_add_u32 v114, v117, 11, v114
	s_lshr_b32 s7, s6, 1
	s_lshl_b32 s7, s7, 6
	s_add_u32 s7, s7, s11
	s_and_b32 s6, s6, 1
	s_lshl_b32 s6, s6, 6
	s_and_b32 s8, s10, 0x3ff
	s_add_u32 s6, s6, s8
	s_cmp_eq_u32 s12, 2
	s_cbranch_scc1 .Lodin4_vseg
	s_cmp_ge_u32 s11, 0x2000
	s_cbranch_scc1 .Lodin4_rope
